# rotK with the bias-table LDS reads issued after the 4th PV MFMA instead of the 1st
# speedup vs baseline: 1.0199x; 1.0199x over previous
; template <int MODE>
; __device__ __forceinline__ void step64(St& S, const bf16x8 (&qf)[4], int t, int qpos0, bool diag, bool first, float cq, float cfar, const LAS float* tab,
;                                        const LAS unsigned char* buf, unsigned vaddr, int r32, int hi) {
;     ...
;         if (qpos0 - (t * 64 + 31) >= 128) {
;             const float c = cfar - S.m;
; #pragma unroll
;             for (int r = 0; r < 16; ++r) sa[r] = c;
;         } else {
;             const int dd = qpos0 + r32 - t * 64 + 128;
; #pragma unroll
;             for (int r = 0; r < 16; ++r) { int idx = dd - crow(r, hi); idx = idx < 0 ? 0 : (idx > 256 ? 256 : idx); sa[r] = tab[idx] - S.m; }
;     ...
;     for (int r = 0; r < 16; ++r) { sa[r] = __builtin_amdgcn_exp2f(sa[r]); sb[r] = __builtin_amdgcn_exp2f(sb[r]); }
;     asm volatile("s_waitcnt lgkmcnt(0)" ::: "memory");
;     __builtin_amdgcn_sched_barrier(0);
;     u32x4 pa0, pa1, pb0, pb1;
;     pa0.x = pk2(sa[0], sa[1]); pa0.y = pk2(sa[2], sa[3]); pa0.z = pk2(sa[4], sa[5]); pa0.w = pk2(sa[6], sa[7]);
;     pa1.x = pk2(sa[8], sa[9]); pa1.y = pk2(sa[10], sa[11]); pa1.z = pk2(sa[12], sa[13]); pa1.w = pk2(sa[14], sa[15]);
;     pb0.x = pk2(sb[0], sb[1]); pb0.y = pk2(sb[2], sb[3]); pb0.z = pk2(sb[4], sb[5]); pb0.w = pk2(sb[6], sb[7]);
;     pb1.x = pk2(sb[8], sb[9]); pb1.y = pk2(sb[10], sb[11]); pb1.z = pk2(sb[12], sb[13]); pb1.w = pk2(sb[14], sb[15]);
;     ...
;     S.o0 = __builtin_amdgcn_mfma_f32_32x32x16_bf16(ATT_VF(0), ATT_PF(pa0), S.o0, 0, 0, 0);
;     S.o1 = __builtin_amdgcn_mfma_f32_32x32x16_bf16(ATT_VF(2), ATT_PF(pa0), S.o1, 0, 0, 0);
;     S.o0 = __builtin_amdgcn_mfma_f32_32x32x16_bf16(ATT_VF(1), ATT_PF(pa1), S.o0, 0, 0, 0);
;     S.o1 = __builtin_amdgcn_mfma_f32_32x32x16_bf16(ATT_VF(3), ATT_PF(pa1), S.o1, 0, 0, 0);
;     S.o0 = __builtin_amdgcn_mfma_f32_32x32x16_bf16(ATT_VF(4), ATT_PF(pb0), S.o0, 0, 0, 0);
;     S.o1 = __builtin_amdgcn_mfma_f32_32x32x16_bf16(ATT_VF(6), ATT_PF(pb0), S.o1, 0, 0, 0);
;     S.o0 = __builtin_amdgcn_mfma_f32_32x32x16_bf16(ATT_VF(5), ATT_PF(pb1), S.o0, 0, 0, 0);
;     S.o1 = __builtin_amdgcn_mfma_f32_32x32x16_bf16(ATT_VF(7), ATT_PF(pb1), S.o1, 0, 0, 0);
;     ...
;     float l0 = 0.f, l1 = 0.f, l2 = 0.f, l3 = 0.f;
; #pragma unroll
;     for (int r = 0; r < 16; r += 2) { l0 += sa[r]; l1 += sa[r + 1]; l2 += sb[r]; l3 += sb[r + 1]; }
;     S.l += (l0 + l1) + (l2 + l3);
.Lk0_nodma:
	s_cmp_le_i32 s44, s34
	s_cbranch_scc1 .Lk0_noY
	s_add_i32 s35, s41, 1
	s_cmp_gt_i32 s44, s35
	s_cbranch_scc1 .Lk0_noY
	v_exp_f32_e32 v48, v48
	v_exp_f32_e32 v49, v49
	v_exp_f32_e32 v50, v50
	v_exp_f32_e32 v51, v51
	v_exp_f32_e32 v52, v52
	v_exp_f32_e32 v53, v53
	v_exp_f32_e32 v54, v54
	v_exp_f32_e32 v55, v55
	v_cvt_pk_bf16_f32 v218, v48, v49
	v_cvt_pk_bf16_f32 v219, v50, v51
	v_cvt_pk_bf16_f32 v220, v52, v53
	v_cvt_pk_bf16_f32 v221, v54, v55
	v_exp_f32_e32 v56, v56
	v_exp_f32_e32 v57, v57
	v_mfma_f32_32x32x16_bf16 v[32:47], v[112:115], v[218:221], v[32:47]
	v_exp_f32_e32 v58, v58
	v_exp_f32_e32 v59, v59
	v_exp_f32_e32 v60, v60
	v_exp_f32_e32 v61, v61
	v_exp_f32_e32 v62, v62
	v_exp_f32_e32 v63, v63
	v_mfma_f32_32x32x16_bf16 v[16:31], v[108:111], v[218:221], v[16:31]
	v_cvt_pk_bf16_f32 v222, v56, v57
	v_cvt_pk_bf16_f32 v223, v58, v59
	v_cvt_pk_bf16_f32 v224, v60, v61
	v_cvt_pk_bf16_f32 v225, v62, v63
	v_add_f32_e32 v0, v48, v50
	v_add_f32_e32 v0, v0, v52
	v_add_f32_e32 v14, v49, v51
	v_add_f32_e32 v14, v14, v53
	v_mfma_f32_32x32x16_bf16 v[32:47], v[104:107], v[222:225], v[32:47]
	v_exp_f32_e32 v64, v64
	v_exp_f32_e32 v65, v65
	v_exp_f32_e32 v66, v66
	v_exp_f32_e32 v67, v67
	v_exp_f32_e32 v68, v68
	v_exp_f32_e32 v69, v69
	v_exp_f32_e32 v70, v70
	v_exp_f32_e32 v71, v71
	v_mfma_f32_32x32x16_bf16 v[16:31], v[100:103], v[222:225], v[16:31]
	s_cmp_gt_i32 s44, s41
	s_cbranch_scc1 .Lk0a_notab
	s_add_i32 s35, s48, 63
	s_min_i32 s35, s35, 192
	s_lshl_b32 s35, s35, 2
	v_subrev_u32_e32 v235, s35, v238
	s_waitcnt lgkmcnt(0)
	ds_read_b128 v[158:161], v235
	ds_read_b128 v[162:165], v235 offset:32
	ds_read_b128 v[166:169], v235 offset:64
	ds_read_b128 v[170:173], v235 offset:96
	ds_read_b128 v[174:177], v235 offset:128
	ds_read_b128 v[180:183], v235 offset:160
	ds_read_b128 v[116:119], v235 offset:192
	ds_read_b64 v[236:237], v235 offset:224
	ds_read_b32 v178, v235 offset:232
	ds_read_b32 v185, v235 offset:236
.Lk0a_notab:
	v_cvt_pk_bf16_f32 v226, v64, v65
	v_cvt_pk_bf16_f32 v227, v66, v67
	v_cvt_pk_bf16_f32 v228, v68, v69
	v_cvt_pk_bf16_f32 v229, v70, v71
	v_add_f32_e32 v0, v0, v54
	v_add_f32_e32 v0, v0, v56
	v_add_f32_e32 v14, v14, v55
	v_add_f32_e32 v14, v14, v57
	v_mfma_f32_32x32x16_bf16 v[32:47], v[96:99], v[226:229], v[32:47]
	v_exp_f32_e32 v72, v72
	v_exp_f32_e32 v73, v73
	v_exp_f32_e32 v74, v74
	v_exp_f32_e32 v75, v75
	v_exp_f32_e32 v76, v76
	v_exp_f32_e32 v77, v77
	v_exp_f32_e32 v78, v78
	v_exp_f32_e32 v79, v79
	v_mfma_f32_32x32x16_bf16 v[16:31], v[10:13], v[226:229], v[16:31]
	v_cvt_pk_bf16_f32 v230, v72, v73
	v_cvt_pk_bf16_f32 v231, v74, v75
	v_cvt_pk_bf16_f32 v232, v76, v77
	v_cvt_pk_bf16_f32 v233, v78, v79
	v_add_f32_e32 v0, v0, v58
	v_add_f32_e32 v0, v0, v60
	v_add_f32_e32 v0, v0, v62
	v_add_f32_e32 v14, v14, v59
	v_add_f32_e32 v14, v14, v61
	v_add_f32_e32 v14, v14, v63
	v_mfma_f32_32x32x16_bf16 v[32:47], v[6:9], v[230:233], v[32:47]
	v_add_f32_e32 v15, v64, v66
	v_add_f32_e32 v15, v15, v68
	v_add_f32_e32 v15, v15, v70
	v_add_f32_e32 v15, v15, v72
	v_add_f32_e32 v234, v65, v67
	v_add_f32_e32 v234, v234, v69
	v_add_f32_e32 v234, v234, v71
	v_add_f32_e32 v234, v234, v73
	v_mfma_f32_32x32x16_bf16 v[16:31], v[2:5], v[230:233], v[16:31]
	v_add_f32_e32 v15, v15, v74
	v_add_f32_e32 v15, v15, v76
	v_add_f32_e32 v15, v15, v78
	v_add_f32_e32 v234, v234, v75
	v_add_f32_e32 v234, v234, v77
	v_add_f32_e32 v234, v234, v79
	v_add_f32_e32 v0, v0, v14
	v_add_f32_e32 v15, v15, v234
	v_add_f32_e32 v0, v0, v15
	v_add_f32_e32 v150, v150, v0
	s_cmp_gt_i32 s44, s41
	s_cbranch_scc1 .Lk0a_end
	s_waitcnt lgkmcnt(0)
	v_sub_f32_e32 v48, v158, v157
	v_sub_f32_e32 v49, v159, v157
	v_sub_f32_e32 v50, v160, v157
	v_sub_f32_e32 v51, v161, v157
	v_sub_f32_e32 v52, v162, v157
	v_sub_f32_e32 v53, v163, v157
	v_sub_f32_e32 v54, v164, v157
	v_sub_f32_e32 v55, v165, v157
	v_sub_f32_e32 v56, v166, v157
	v_sub_f32_e32 v57, v167, v157
	v_sub_f32_e32 v58, v168, v157
	v_sub_f32_e32 v59, v169, v157
	v_sub_f32_e32 v60, v170, v157
	v_sub_f32_e32 v61, v171, v157
	v_sub_f32_e32 v62, v172, v157
	v_sub_f32_e32 v63, v173, v157
	v_sub_f32_e32 v64, v174, v157
	v_sub_f32_e32 v65, v175, v157
	v_sub_f32_e32 v66, v176, v157
	v_sub_f32_e32 v67, v177, v157
	v_sub_f32_e32 v68, v180, v157
	v_sub_f32_e32 v69, v181, v157
	v_sub_f32_e32 v70, v182, v157
	v_sub_f32_e32 v71, v183, v157
	v_sub_f32_e32 v72, v116, v157
	v_sub_f32_e32 v73, v117, v157
	v_sub_f32_e32 v74, v118, v157
	v_sub_f32_e32 v75, v119, v157
	v_sub_f32_e32 v76, v236, v157
	v_sub_f32_e32 v77, v237, v157
	v_sub_f32_e32 v78, v178, v157
	v_sub_f32_e32 v79, v185, v157

; __device__ __forceinline__ unsigned pk2(float lo, float hi) { f32x2_t v = {lo, hi}; bf16x2_t b = __builtin_convertvector(v, bf16x2_t); return __builtin_bit_cast(unsigned, b); }
; template <int MODE>
; __device__ __forceinline__ void step64(St& S, const bf16x8 (&qf)[4], int t, int qpos0, bool diag, bool first, float cq, float cfar, const LAS float* tab,
;                                        const LAS unsigned char* buf, unsigned vaddr, int r32, int hi) {
;     ...
;     for (int r = 0; r < 16; ++r) { sa[r] = __builtin_amdgcn_exp2f(sa[r]); sb[r] = __builtin_amdgcn_exp2f(sb[r]); }
;     asm volatile("s_waitcnt lgkmcnt(0)" ::: "memory");
;     __builtin_amdgcn_sched_barrier(0);
;     u32x4 pa0, pa1, pb0, pb1;
;     pa0.x = pk2(sa[0], sa[1]); pa0.y = pk2(sa[2], sa[3]); pa0.z = pk2(sa[4], sa[5]); pa0.w = pk2(sa[6], sa[7]);
;     pa1.x = pk2(sa[8], sa[9]); pa1.y = pk2(sa[10], sa[11]); pa1.z = pk2(sa[12], sa[13]); pa1.w = pk2(sa[14], sa[15]);
;     pb0.x = pk2(sb[0], sb[1]); pb0.y = pk2(sb[2], sb[3]); pb0.z = pk2(sb[4], sb[5]); pb0.w = pk2(sb[6], sb[7]);
;     pb1.x = pk2(sb[8], sb[9]); pb1.y = pk2(sb[10], sb[11]); pb1.z = pk2(sb[12], sb[13]); pb1.w = pk2(sb[14], sb[15]);
;     ...
;     S.o0 = __builtin_amdgcn_mfma_f32_32x32x16_bf16(ATT_VF(0), ATT_PF(pa0), S.o0, 0, 0, 0);
;     S.o1 = __builtin_amdgcn_mfma_f32_32x32x16_bf16(ATT_VF(2), ATT_PF(pa0), S.o1, 0, 0, 0);
;     S.o0 = __builtin_amdgcn_mfma_f32_32x32x16_bf16(ATT_VF(1), ATT_PF(pa1), S.o0, 0, 0, 0);
;     S.o1 = __builtin_amdgcn_mfma_f32_32x32x16_bf16(ATT_VF(3), ATT_PF(pa1), S.o1, 0, 0, 0);
.Lk0_epi:
	s_add_i32 s35, s41, 1
	s_cmp_gt_i32 s44, s35
	s_cbranch_scc1 .Lk0_done
	v_exp_f32_e32 v48, v48
	v_exp_f32_e32 v49, v49
	v_exp_f32_e32 v50, v50
	v_exp_f32_e32 v51, v51
	v_exp_f32_e32 v52, v52
	v_exp_f32_e32 v53, v53
	v_exp_f32_e32 v54, v54
	v_exp_f32_e32 v55, v55
	v_cvt_pk_bf16_f32 v218, v48, v49
	v_cvt_pk_bf16_f32 v219, v50, v51
	v_cvt_pk_bf16_f32 v220, v52, v53
	v_cvt_pk_bf16_f32 v221, v54, v55
	v_exp_f32_e32 v56, v56
	v_exp_f32_e32 v57, v57
	v_mfma_f32_32x32x16_bf16 v[32:47], v[112:115], v[218:221], v[32:47]
	v_exp_f32_e32 v58, v58
	v_exp_f32_e32 v59, v59
	v_exp_f32_e32 v60, v60
	v_exp_f32_e32 v61, v61
	v_exp_f32_e32 v62, v62
	v_exp_f32_e32 v63, v63
	v_mfma_f32_32x32x16_bf16 v[16:31], v[108:111], v[218:221], v[16:31]
	v_cvt_pk_bf16_f32 v222, v56, v57
	v_cvt_pk_bf16_f32 v223, v58, v59
	v_cvt_pk_bf16_f32 v224, v60, v61
	v_cvt_pk_bf16_f32 v225, v62, v63
	v_add_f32_e32 v0, v48, v50
	v_add_f32_e32 v0, v0, v52
	v_add_f32_e32 v14, v49, v51
	v_add_f32_e32 v14, v14, v53
	v_mfma_f32_32x32x16_bf16 v[32:47], v[104:107], v[222:225], v[32:47]
	v_exp_f32_e32 v64, v64
	v_exp_f32_e32 v65, v65
	v_exp_f32_e32 v66, v66
	v_exp_f32_e32 v67, v67
	v_exp_f32_e32 v68, v68
	v_exp_f32_e32 v69, v69
	v_exp_f32_e32 v70, v70
	v_exp_f32_e32 v71, v71
	v_mfma_f32_32x32x16_bf16 v[16:31], v[100:103], v[222:225], v[16:31]
	s_cmp_gt_i32 s44, s41
	s_cbranch_scc1 .Lk0b_notab
	s_add_i32 s35, s48, 63
	s_min_i32 s35, s35, 192
	s_lshl_b32 s35, s35, 2
	v_subrev_u32_e32 v235, s35, v238
	s_waitcnt lgkmcnt(0)
	ds_read_b128 v[158:161], v235
	ds_read_b128 v[162:165], v235 offset:32
	ds_read_b128 v[166:169], v235 offset:64
	ds_read_b128 v[170:173], v235 offset:96
	ds_read_b128 v[174:177], v235 offset:128
	ds_read_b128 v[180:183], v235 offset:160
	ds_read_b128 v[116:119], v235 offset:192
	ds_read_b64 v[236:237], v235 offset:224
	ds_read_b32 v178, v235 offset:232
	ds_read_b32 v185, v235 offset:236
